# late weight transposes (tail of the first GEMM phase): next w_in tile's loads issued before the current tile's LDS read/pack/store half, which runs on private registers
# baseline (speedup 1.0000x reference)
.LBB0_159:
	s_mul_i32 s0, s72, -12
	s_add_i32 s4, s0, 0xc40
	s_cmp_gt_i32 s4, 0
	s_cselect_b64 s[0:1], -1, 0
	s_cmp_lt_i32 s4, s72
	s_cselect_b64 s[2:3], -1, 0
	s_and_b64 s[0:1], s[0:1], s[2:3]
	s_and_b64 s[0:1], s[0:1], exec
	s_cselect_b32 s0, s4, 0
	s_cmp_lt_i32 s55, s0
	s_cbranch_scc1 .LBB0_203
	s_sub_i32 s2, s55, s0
	s_cmpk_gt_i32 s2, 0x9ff
	s_waitcnt vmcnt(0) lgkmcnt(0)
	s_barrier
	s_cbranch_scc1 .LBB0_203
	v_lshlrev_b32_e32 v0, 2, v164
	v_and_b32_e32 v44, 0x7c, v0
	v_lshlrev_b32_e32 v0, 3, v164
	s_lshl_b32 s1, s55, 3
	s_lshl_b32 s4, s0, 3
	v_and_b32_e32 v4, 0x78, v0
	s_sub_i32 s8, s1, s4
	s_lshl_b32 s1, s72, 3
	v_lshlrev_b32_e32 v32, 1, v4
	v_mov_b32_e32 v33, 0
	s_sub_i32 s9, s1, s4
	s_lshl_b32 s1, s55, 7
	s_lshl_b32 s4, s0, 7
	v_lshl_add_u64 v[0:1], s[82:83], 0, v[32:33]
	s_mov_b64 s[6:7], 0x7900000
	v_add_u32_e32 v6, 0x200, v164
	v_add_u32_e32 v7, 0x600, v164
	s_sub_i32 s10, s1, s4
	s_lshl_b32 s1, s72, 7
	s_sub_i32 s3, s72, s0
	v_lshrrev_b32_e32 v45, 5, v164
	v_lshl_add_u64 v[34:35], v[0:1], 0, s[6:7]
	v_lshrrev_b32_e32 v46, 4, v164
	v_lshrrev_b32_e32 v47, 4, v6
	v_lshrrev_b32_e32 v49, 4, v7
	s_mov_b64 s[6:7], 0x7100000
	s_sub_i32 s11, s1, s4
	s_lshl_b32 s1, s55, 2
	s_lshl_b32 s0, s0, 2
	v_lshl_add_u32 v2, v44, 2, 0
	v_mul_u32_u24_e32 v3, 0x204, v45
	v_mul_u32_u24_e32 v4, 0x204, v4
	v_lshl_add_u32 v5, v46, 2, 0
	v_lshl_add_u32 v6, v47, 2, 0
	v_lshl_add_u32 v7, v49, 2, 0
	v_lshl_add_u64 v[36:37], v[0:1], 0, s[6:7]
	s_mov_b64 s[6:7], 0x6100000
	s_sub_i32 s1, s1, s0
	v_lshl_add_u64 v[38:39], v[0:1], 0, s[6:7]
	s_mov_b64 s[6:7], 0x3100000
	s_add_i32 s12, s1, 0x7fffe800
	s_lshl_b32 s1, s72, 2
	v_add_u32_e32 v50, v2, v3
	v_add_u32_e32 v65, v5, v4
	v_add_u32_e32 v66, v6, v4
	v_add_u32_e32 v67, v7, v4
	s_mov_b32 s5, 0
	v_or_b32_e32 v48, 64, v46
	v_lshl_add_u64 v[40:41], v[0:1], 0, s[6:7]
	s_sub_i32 s13, s1, s0
	v_add_u32_e32 v51, 0x2040, v50
	v_add_u32_e32 v52, 0x2048, v50
	v_add_u32_e32 v53, 0x4080, v50
	v_add_u32_e32 v54, 0x4088, v50
	v_add_u32_e32 v55, 0x60c0, v50
	v_add_u32_e32 v56, 0x60c8, v50
	v_add_u32_e32 v57, 0x8100, v50
	v_add_u32_e32 v58, 0x8108, v50
	v_add_u32_e32 v59, 0xa140, v50
	v_add_u32_e32 v60, 0xa148, v50
	v_add_u32_e32 v61, 0xc180, v50
	v_add_u32_e32 v62, 0xc188, v50
	v_add_u32_e32 v63, 0xe1c0, v50
	v_add_u32_e32 v64, 0xe1c8, v50
	s_movk_i32 s18, 0xfff
	s_movk_i32 s19, 0x7f
	v_add_u32_e32 v68, 8, v65
	v_add_u32_e32 v69, 12, v65
	v_add_u32_e32 v70, 16, v65
	v_add_u32_e32 v71, 20, v65
	v_add_u32_e32 v72, 24, v65
	v_add_u32_e32 v73, 28, v65
	v_add_u32_e32 v74, 0x400, v66
	v_add_u32_e32 v75, 0x800, v66
	v_add_u32_e32 v76, 0xc00, v66
	v_add_u32_e32 v77, 0x400, v67
	v_add_u32_e32 v78, 0x800, v67
	v_add_u32_e32 v79, 0xc00, v67
	s_branch .LBB0_164
.LBB0_163:
	s_add_i32 s2, s2, s3
	s_add_i32 s8, s8, s9
	s_add_i32 s10, s10, s11
	s_add_i32 s12, s12, s13
	s_cmpk_lt_i32 s2, 0xa00
	s_cbranch_scc0 .LBB0_203

.LBB0_174:
	s_andn2_b64 vcc, exec, s[0:1]
	s_cbranch_vccnz .LBB0_163
	s_mov_b32 s86, 0
.Llt_load:
	s_and_b32 s20, s8, 0xffffff80
	v_or_b32_e32 v0, s20, v44
	v_cmp_lt_i32_e32 vcc, s18, v0
	s_and_saveexec_b64 s[0:1], vcc
	s_xor_b64 s[0:1], exec, s[0:1]
	s_cbranch_execz .LBB0_185
	s_cmpk_gt_u32 s8, 0x1fff
	s_mov_b64 s[6:7], -1
	s_cbranch_scc0 .LBB0_178
	v_add_u32_e32 v32, 0x3050, v0
	s_mov_b64 s[6:7], 0

.LBB0_162:
	s_or_b64 exec, exec, s[6:7]
	s_cmp_eq_u32 s86, 0
	s_cbranch_scc0 .Llt_finish
	s_waitcnt vmcnt(0)
	s_branch .Llt_proc1b

.Llt_proc1b:
	ds_write2_b32 v50, v0, v1 offset1:1
	ds_write2_b32 v50, v2, v3 offset0:2 offset1:3
	ds_write2_b32 v51, v4, v5 offset1:1
	ds_write2_b32 v52, v6, v7 offset1:1
	ds_write2_b32 v53, v12, v13 offset1:1
	ds_write2_b32 v54, v14, v15 offset1:1
	ds_write2_b32 v55, v8, v9 offset1:1
	ds_write2_b32 v56, v10, v11 offset1:1
	ds_write2_b32 v57, v20, v21 offset1:1
	ds_write2_b32 v58, v22, v23 offset1:1
	ds_write2_b32 v59, v16, v17 offset1:1
	ds_write2_b32 v60, v18, v19 offset1:1
	ds_write2_b32 v61, v28, v29 offset1:1
	ds_write2_b32 v62, v30, v31 offset1:1
	ds_write2_b32 v63, v24, v25 offset1:1
	ds_write2_b32 v64, v26, v27 offset1:1
	s_lshl_b32 s88, s4, 1
	s_mov_b32 s89, 0
	s_mov_b32 s90, s20
	s_mov_b32 s86, 1
	s_add_i32 s2, s2, s3
	s_add_i32 s8, s8, s9
	s_add_i32 s10, s10, s11
	s_add_i32 s12, s12, s13
	s_mov_b32 s87, 0
	s_cmpk_gt_i32 s2, 0x5ff
	s_cbranch_scc1 .Llt_finish
	s_mov_b32 s87, 1
	s_branch .Llt_load
.Llt_finish:
	s_waitcnt lgkmcnt(0)
	s_barrier
	ds_read2st64_b32 v[104:105], v65 offset1:1
	ds_read2_b32 v[106:107], v65 offset0:129 offset1:193
	ds_read2st64_b32 v[108:109], v68 offset0:4 offset1:5
	ds_read2st64_b32 v[110:111], v69 offset0:6 offset1:7
	ds_read2st64_b32 v[112:113], v70 offset0:8 offset1:9
	ds_read2st64_b32 v[114:115], v71 offset0:10 offset1:11
	ds_read2st64_b32 v[116:117], v72 offset0:12 offset1:13
	ds_read2st64_b32 v[118:119], v73 offset0:14 offset1:15
	v_or_b32_e32 v122, s90, v46
	v_ashrrev_i32_e32 v123, 31, v122
	v_lshl_add_u64 v[120:121], v[40:41], 0, s[88:89]
	v_lshlrev_b64 v[122:123], 12, v[122:123]
	ds_read2_b32 v[124:125], v66 offset1:129
	ds_read2_b32 v[126:127], v74 offset0:2 offset1:131
	ds_read2_b32 v[128:129], v75 offset0:4 offset1:133
	ds_read2_b32 v[130:131], v76 offset0:6 offset1:135
	s_waitcnt lgkmcnt(10)
	v_cvt_pk_bf16_f32 v100, v104, v106
	s_waitcnt lgkmcnt(8)
	v_cvt_pk_bf16_f32 v101, v108, v110
	s_waitcnt lgkmcnt(6)
	v_cvt_pk_bf16_f32 v102, v112, v114
	s_waitcnt lgkmcnt(4)
	v_cvt_pk_bf16_f32 v103, v116, v118
	v_lshl_add_u64 v[122:123], v[120:121], 0, v[122:123]
	global_store_dwordx4 v[122:123], v[100:103], off
	v_or_b32_e32 v122, s90, v47
	v_ashrrev_i32_e32 v123, 31, v122
	v_lshlrev_b64 v[122:123], 12, v[122:123]
	s_waitcnt lgkmcnt(3)
	v_cvt_pk_bf16_f32 v100, v124, v125
	s_waitcnt lgkmcnt(2)
	v_cvt_pk_bf16_f32 v101, v126, v127
	s_waitcnt lgkmcnt(1)
	v_cvt_pk_bf16_f32 v102, v128, v129
	s_waitcnt lgkmcnt(0)
	v_cvt_pk_bf16_f32 v103, v130, v131
	v_lshl_add_u64 v[122:123], v[120:121], 0, v[122:123]
	v_or_b32_e32 v104, s90, v48
	global_store_dwordx4 v[122:123], v[100:103], off
	s_nop 1
	v_cvt_pk_bf16_f32 v100, v105, v107
	v_ashrrev_i32_e32 v105, 31, v104
	v_cvt_pk_bf16_f32 v101, v109, v111
	v_cvt_pk_bf16_f32 v102, v113, v115
	v_lshlrev_b64 v[104:105], 12, v[104:105]
	ds_read2_b32 v[106:107], v67 offset1:129
	ds_read2_b32 v[108:109], v77 offset0:2 offset1:131
	ds_read2_b32 v[110:111], v78 offset0:4 offset1:133
	ds_read2_b32 v[112:113], v79 offset0:6 offset1:135
	v_cvt_pk_bf16_f32 v103, v117, v119
	v_lshl_add_u64 v[104:105], v[120:121], 0, v[104:105]
	global_store_dwordx4 v[104:105], v[100:103], off
	v_add_u32_e32 v104, s90, v49
	v_ashrrev_i32_e32 v105, 31, v104
	v_lshlrev_b64 v[104:105], 12, v[104:105]
	s_waitcnt lgkmcnt(3)
	v_cvt_pk_bf16_f32 v100, v106, v107
	s_waitcnt lgkmcnt(2)
	v_cvt_pk_bf16_f32 v101, v108, v109
	s_waitcnt lgkmcnt(1)
	v_cvt_pk_bf16_f32 v102, v110, v111
	s_waitcnt lgkmcnt(0)
	v_cvt_pk_bf16_f32 v103, v112, v113
	v_lshl_add_u64 v[104:105], v[120:121], 0, v[104:105]
	global_store_dwordx4 v[104:105], v[100:103], off
	s_barrier
	s_cmp_eq_u32 s87, 1
	s_cbranch_scc1 .Llt_proc1
	s_cmpk_lt_i32 s2, 0xa00
	s_cbranch_scc0 .LBB0_203
	s_branch .LBB0_164
